# combined + E1: softmax VALU restructured for ILP (v_max3 tree, 4 partial row sums)
# baseline (speedup 1.0000x reference)
; __device__ __forceinline__ void partialSM(f32x16& p0, f32x16& p1, float& m_reg, float& mn, float& alpha) {
;     float pmax = p0[0]; for (int r = 1; r < 16; ++r) pmax = fmaxf(pmax, p0[r]); for (int r = 0; r < 16; ++r) pmax = fmaxf(pmax, p1[r]);
;     { auto rr = __builtin_amdgcn_permlane32_swap(__float_as_uint(pmax), __float_as_uint(pmax), false, false);
;       pmax = fmaxf(__uint_as_float(rr[0]), __uint_as_float(rr[1])); }
;     constexpr float C2 = 1.4426950408889634f * SCALE;
;     if (__builtin_expect(__all((pmax - m_reg) * SCALE <= THR), 1)) { mn = m_reg; alpha = 1.f; }
;     else { mn = fmaxf(m_reg, pmax); alpha = __builtin_amdgcn_exp2f((m_reg - mn) * C2); m_reg = mn; }
;     const float mnL = -mn * C2;
;     for (int r = 0; r < 16; ++r) p0[r] = fmaf(p0[r], C2, mnL); for (int r = 0; r < 16; ++r) p1[r] = fmaf(p1[r], C2, mnL);
;     for (int r = 0; r < 16; ++r) p0[r] = __builtin_amdgcn_exp2f(p0[r]);
; }
; __device__ __forceinline__ void finishSM(f32x16& p0, f32x16& p1, float alpha, float& l_reg, bf16x8& pa0, bf16x8& pa1, bf16x8& pa2, bf16x8& pa3) {
;     for (int r = 0; r < 16; ++r) p1[r] = __builtin_amdgcn_exp2f(p1[r]);
;     float ps = 0; for (int r = 0; r < 16; ++r) ps += p0[r]; for (int r = 0; r < 16; ++r) ps += p1[r];
;     { auto rr = __builtin_amdgcn_permlane32_swap(__float_as_uint(ps), __float_as_uint(ps), false, false);
;       ps = __uint_as_float(rr[0]) + __uint_as_float(rr[1]); }
;     l_reg = l_reg * alpha + ps;
;     ...
;     PK4(p0, 0, pa0); PK4(p0, 8, pa1); PK4(p1, 0, pa2); PK4(p1, 8, pa3);
;     ...
; }
; __device__ __forceinline__ void attn2_block(const Blk& c, char* lds) {
;     ...
;                 att::partialSM(p0, p1, m_reg, mn, al);
;                 att::finishSM(p0, p1, al, l_reg, pa0, pa1, pa2, pa3);
;                 char* pw = Pb + par * 4096 + lane * 16;
;                 *(bf16x8*)(pw) = pa0; *(bf16x8*)(pw + 1024) = pa1; *(bf16x8*)(pw + 2048) = pa2; *(bf16x8*)(pw + 3072) = pa3;
;                 if (hi == 0) ALb[par * 32 + r32] = al;
;                 const bool resc = __any(al < 1.f);
;                 if (lane == 0) FLb[par] = resc ? 1u : 0u;
.LBB0_586:
	s_nop 7
	v_max3_f32 v36, v20, v21, v22
	v_max3_f32 v38, v23, v24, v25
	v_max3_f32 v39, v26, v27, v28
	v_max3_f32 v40, v29, v30, v31
	v_max3_f32 v41, v32, v33, v34
	v_max3_f32 v42, v4, v5, v6
	v_max3_f32 v43, v7, v8, v9
	v_max3_f32 v44, v10, v11, v12
	v_max3_f32 v45, v13, v14, v15
	v_max3_f32 v46, v16, v17, v18
	v_max3_f32 v36, v36, v38, v39
	v_max3_f32 v40, v40, v41, v35
	v_max3_f32 v42, v42, v43, v44
	v_max3_f32 v45, v45, v46, v19
	v_max3_f32 v36, v36, v40, v42
	v_max_f32_e32 v36, v36, v45
	v_mov_b32_e32 v37, v36
	s_nop 1
	v_permlane32_swap_b32_e32 v36, v37
	v_max_f32_e32 v36, v36, v37
	v_sub_f32_e32 v37, v36, v113
	v_mul_f32_e32 v37, 0x3db504f3, v37
	v_cmp_ge_f32_e32 vcc, s48, v37
	v_max_f32_e32 v38, v113, v36
	s_cmp_eq_u64 vcc, exec
	s_cselect_b64 vcc, -1, 0
	v_sub_f32_e32 v36, v113, v38
	v_cndmask_b32_e32 v113, v38, v113, vcc
	v_mul_f32_e32 v37, 0xbe0293ee, v113
	v_fmamk_f32 v20, v20, 0x3e0293ee, v37
	v_fmamk_f32 v21, v21, 0x3e0293ee, v37
	v_fmamk_f32 v22, v22, 0x3e0293ee, v37
	v_fmamk_f32 v23, v23, 0x3e0293ee, v37
	v_fmamk_f32 v24, v24, 0x3e0293ee, v37
	v_fmamk_f32 v25, v25, 0x3e0293ee, v37
	v_fmamk_f32 v26, v26, 0x3e0293ee, v37
	v_fmamk_f32 v27, v27, 0x3e0293ee, v37
	v_fmamk_f32 v28, v28, 0x3e0293ee, v37
	v_fmamk_f32 v29, v29, 0x3e0293ee, v37
	v_fmamk_f32 v30, v30, 0x3e0293ee, v37
	v_fmamk_f32 v31, v31, 0x3e0293ee, v37
	v_fmamk_f32 v32, v32, 0x3e0293ee, v37
	v_fmamk_f32 v33, v33, 0x3e0293ee, v37
	v_fmamk_f32 v34, v34, 0x3e0293ee, v37
	v_fmamk_f32 v35, v35, 0x3e0293ee, v37
	v_fmamk_f32 v4, v4, 0x3e0293ee, v37
	v_fmamk_f32 v5, v5, 0x3e0293ee, v37
	v_fmamk_f32 v6, v6, 0x3e0293ee, v37
	v_fmamk_f32 v7, v7, 0x3e0293ee, v37
	v_fmamk_f32 v8, v8, 0x3e0293ee, v37
	v_fmamk_f32 v9, v9, 0x3e0293ee, v37
	v_fmamk_f32 v10, v10, 0x3e0293ee, v37
	v_fmamk_f32 v11, v11, 0x3e0293ee, v37
	v_fmamk_f32 v12, v12, 0x3e0293ee, v37
	v_fmamk_f32 v13, v13, 0x3e0293ee, v37
	v_fmamk_f32 v14, v14, 0x3e0293ee, v37
	v_fmamk_f32 v15, v15, 0x3e0293ee, v37
	v_fmamk_f32 v16, v16, 0x3e0293ee, v37
	v_fmamk_f32 v17, v17, 0x3e0293ee, v37
	v_fmamk_f32 v18, v18, 0x3e0293ee, v37
	v_fmac_f32_e32 v37, 0x3e0293ee, v19
	v_exp_f32_e32 v19, v20
	v_exp_f32_e32 v20, v21
	v_exp_f32_e32 v21, v22
	v_exp_f32_e32 v22, v23
	v_exp_f32_e32 v23, v24
	v_exp_f32_e32 v24, v25
	v_add_f32_e32 v60, v19, v23
	v_exp_f32_e32 v25, v26
	v_add_f32_e32 v61, v20, v24
	v_exp_f32_e32 v26, v27
	v_add_f32_e32 v62, v21, v25
	v_exp_f32_e32 v27, v28
	v_add_f32_e32 v63, v22, v26
	v_exp_f32_e32 v28, v29
	v_add_f32_e32 v60, v27, v60
	v_exp_f32_e32 v29, v30
	v_add_f32_e32 v61, v28, v61
	v_exp_f32_e32 v30, v31
	v_add_f32_e32 v62, v29, v62
	v_exp_f32_e32 v31, v32
	v_add_f32_e32 v63, v30, v63
	v_exp_f32_e32 v32, v33
	v_add_f32_e32 v60, v31, v60
	v_exp_f32_e32 v33, v34
	v_add_f32_e32 v61, v32, v61
	v_exp_f32_e32 v34, v35
	v_add_f32_e32 v62, v33, v62
	v_exp_f32_e32 v35, v4
	v_add_f32_e32 v63, v34, v63
	v_exp_f32_e32 v38, v5
	v_add_f32_e32 v60, v35, v60
	v_exp_f32_e32 v39, v6
	v_add_f32_e32 v61, v38, v61
	v_exp_f32_e32 v40, v7
	v_add_f32_e32 v62, v39, v62
	v_exp_f32_e32 v41, v8
	v_add_f32_e32 v63, v40, v63
	v_exp_f32_e32 v42, v9
	v_add_f32_e32 v60, v41, v60
	v_exp_f32_e32 v43, v10
	v_add_f32_e32 v61, v42, v61
	v_exp_f32_e32 v44, v11
	v_add_f32_e32 v62, v43, v62
	v_exp_f32_e32 v45, v12
	v_add_f32_e32 v63, v44, v63
	v_exp_f32_e32 v46, v13
	v_add_f32_e32 v60, v45, v60
	v_exp_f32_e32 v47, v14
	v_add_f32_e32 v61, v46, v61
	v_exp_f32_e32 v48, v15
	v_add_f32_e32 v62, v47, v62
	v_exp_f32_e32 v49, v16
	v_add_f32_e32 v63, v48, v63
	v_exp_f32_e32 v50, v17
	v_add_f32_e32 v60, v49, v60
	v_exp_f32_e32 v51, v18
	v_add_f32_e32 v61, v50, v61
	v_exp_f32_e32 v37, v37
	v_add_f32_e32 v62, v51, v62
	v_mul_f32_e32 v36, 0x3e0293ee, v36
	v_exp_f32_e32 v36, v36
	v_add_f32_e32 v63, v37, v63
	v_add_f32_e32 v60, v60, v61
	v_add_f32_e32 v62, v62, v63
	v_add_f32_e32 v4, v60, v62
	v_mov_b32_e32 v5, v4
	v_cvt_pk_bf16_f32 v6, v19, v20
	v_cvt_pk_bf16_f32 v7, v21, v22
	v_cvt_pk_bf16_f32 v8, v23, v24
	v_cvt_pk_bf16_f32 v9, v25, v26
	v_cndmask_b32_e64 v36, v36, 1.0, vcc
	s_nop 0
	v_permlane32_swap_b32_e32 v4, v5
	v_permlane32_swap_b32_e32 v6, v8
	v_permlane32_swap_b32_e32 v7, v9
	v_cvt_pk_bf16_f32 v10, v27, v28
	v_cvt_pk_bf16_f32 v11, v29, v30
	v_cvt_pk_bf16_f32 v12, v31, v32
	v_cvt_pk_bf16_f32 v13, v33, v34
	v_cvt_pk_bf16_f32 v14, v35, v38
	v_cvt_pk_bf16_f32 v15, v39, v40
	v_cvt_pk_bf16_f32 v16, v41, v42
	v_cvt_pk_bf16_f32 v17, v43, v44
	v_cvt_pk_bf16_f32 v18, v45, v46
	v_cvt_pk_bf16_f32 v19, v47, v48
	v_cvt_pk_bf16_f32 v20, v49, v50
	v_cvt_pk_bf16_f32 v21, v51, v37
	v_lshl_add_u32 v22, s88, 12, v112
	v_permlane32_swap_b32_e32 v10, v12
	v_permlane32_swap_b32_e32 v11, v13
	v_permlane32_swap_b32_e32 v14, v16
	v_permlane32_swap_b32_e32 v15, v17
	v_permlane32_swap_b32_e32 v18, v20
	v_permlane32_swap_b32_e32 v19, v21
	ds_write_b128 v22, v[6:9]
	ds_write_b128 v22, v[10:13] offset:1024
	ds_write_b128 v22, v[14:17] offset:2048
	ds_write_b128 v22, v[18:21] offset:3072
	s_and_saveexec_b64 s[16:17], s[2:3]
	v_lshl_add_u32 v6, s88, 7, v2
	ds_write_b32 v6, v36
	s_or_b64 exec, exec, s[16:17]
	v_cmp_gt_f32_e32 vcc, 1.0, v36
	s_and_saveexec_b64 s[16:17], s[4:5]
	s_cbranch_execz .LBB0_590
	s_cmp_lg_u64 vcc, 0
	s_cselect_b64 s[90:91], -1, 0
	s_lshl_b32 s10, s88, 2
	s_add_i32 s10, s79, s10
	v_cndmask_b32_e64 v6, 0, 1, s[90:91]
	v_mov_b32_e32 v7, s10
	ds_write_b32 v7, v6
